# replace cg grid.sync after prologue with copy of the xcd two-level barrier
# speedup vs baseline: 1.0118x; 1.0118x over previous
.LBB0_186:
.Lgs0_224:
	s_waitcnt vmcnt(0)
	s_waitcnt vmcnt(0)
	s_waitcnt lgkmcnt(0)
	s_barrier
	s_mov_b64 s[4:5], exec
	v_readlane_b32 s6, v255, 0
	v_readlane_b32 s7, v255, 1
	s_and_b64 s[6:7], s[4:5], s[6:7]
	s_mov_b64 exec, s[6:7]
	s_cbranch_execz .Lgs0_276
	s_add_i32 s3, 0, 0x257d0
	v_mov_b32_e32 v0, s3
	s_waitcnt vmcnt(0) expcnt(0) lgkmcnt(0)
	ds_read_b32 v2, v0
	s_add_i32 s3, 0, 0x257d4
	v_mov_b32_e32 v0, s3
	ds_read_b32 v0, v0
	s_waitcnt lgkmcnt(1)
	v_cmp_ne_u32_e32 vcc, 0, v2
	s_cbranch_vccnz .Lgs0_240
	s_add_u32 s6, s30, 0x4200
	s_addc_u32 s7, s31, 0
	s_add_u32 s8, s30, 0x4400
	s_addc_u32 s9, s31, 0
	s_add_u32 s10, s30, 0x4500
	s_addc_u32 s11, s31, 0
	s_add_u32 s12, s30, 0x4600
	s_addc_u32 s13, s31, 0
	s_add_u32 s14, s30, 0x4700
	s_addc_u32 s15, s31, 0
	s_add_u32 s16, s30, 0x4800
	s_addc_u32 s17, s31, 0
	s_add_u32 s20, s30, 0x4900
	s_addc_u32 s21, s31, 0
	s_add_u32 s22, s30, 0x4a00
	s_addc_u32 s23, s31, 0
	s_add_u32 s24, s30, 0x4b00
	s_addc_u32 s25, s31, 0
	s_add_u32 s46, s30, 0x4c00
	s_addc_u32 s47, s31, 0
	s_add_u32 s48, s30, 0x4d00
	s_addc_u32 s49, s31, 0
	s_add_u32 s52, s30, 0x4e00
	s_addc_u32 s53, s31, 0
	s_add_u32 s54, s30, 0x4f00
	s_addc_u32 s55, s31, 0
	s_add_u32 s56, s30, 0x5000
	s_load_dword s3, s[0:1], 0x148
	s_addc_u32 s57, s31, 0
	s_add_u32 s58, s30, 0x5100
	s_addc_u32 s59, s31, 0
	s_add_u32 s60, s30, 0x5200
	s_addc_u32 s61, s31, 0
	s_waitcnt lgkmcnt(0)
	s_mul_i32 s3, s29, s3
	s_add_u32 s62, s30, 0x5300
	s_mul_i32 s3, s3, s28
	s_addc_u32 s63, s31, 0
	s_mov_b32 s26, 1
	v_mov_b32_e32 v16, 0
	s_branch .Lgs0_228

.Lgs0_275:
	s_or_b64 exec, exec, s[10:11]
	s_waitcnt vmcnt(0)
.Lgs0_276:
	s_or_b64 exec, exec, s[4:5]
	s_add_u32 s38, s30, 0x5894800
	s_addc_u32 s39, s31, 0
	s_add_u32 s42, s30, 0x7cbc800
	s_addc_u32 s43, s31, 0
	s_add_u32 s44, s30, 0x7994800
	s_addc_u32 s45, s31, 0
	s_add_u32 s40, s30, 0x7cac800
	s_addc_u32 s41, s31, 0
	s_cmpk_lt_i32 s2, 0x5ac
	s_cselect_b64 s[4:5], -1, 0
	v_mov_b32_e32 v8, v210
	v_writelane_b32 v255, s4, 2
	s_barrier
	s_nop 0
	v_writelane_b32 v255, s5, 3
	s_cmpk_gt_i32 s2, 0x5ab
	v_readfirstlane_b32 s12, v8
	s_cbranch_scc1 .LBB0_224
	s_ashr_i32 s3, s2, 31
	s_lshr_b32 s4, s3, 29
	s_add_i32 s7, s2, s4
	s_and_b32 s4, s7, -8
	s_sub_i32 s8, s2, s4
	s_cmp_gt_i32 s8, 3
	s_cbranch_scc0 .LBB0_199
	s_mul_i32 s4, s8, 0xb5
	s_add_i32 s6, s4, 4
	s_cbranch_execz .LBB0_200
	s_branch .LBB0_201
